# GLU epilogue: bias folded into the accumulators up front, its registers reused so that 8 chunks of ya0+z loads are in flight instead of 6
# speedup vs baseline: 1.0043x; 1.0043x over previous
.LBB0_853:
	v_lshl_add_u32 v143, s44, 8, v146
	v_lshl_or_b32 v144, s35, 8, v148
	v_lshlrev_b32_e32 v145, 2, v144
	v_lshlrev_b32_e32 v140, 11, v143
	v_lshl_add_u32 v140, v144, 1, v140
	v_mov_b32_e32 v142, v140
	v_mul_u32_u24_e32 v141, s78, v143
	v_lshl_add_u32 v141, v144, 1, v141
	v_readlane_b32 s2, v251, 14
	v_readlane_b32 s3, v251, 15
	v_readlane_b32 s16, v253, 41
	v_readlane_b32 s17, v253, 42
	s_nop 4
	global_load_dwordx4 v[224:227], v145, s[4:5]
	global_load_dwordx4 v[228:231], v145, s[4:5] offset:16
	global_load_dwordx4 v[232:235], v145, s[4:5] offset:512
	global_load_dwordx4 v[236:239], v145, s[4:5] offset:528
	global_load_dwordx4 v[150:153], v140, s[52:53]
	global_load_dwordx4 v[154:157], v141, s[2:3] offset:2048
	global_load_dwordx4 v[158:161], v140, s[52:53] offset:256
	global_load_dwordx4 v[162:165], v141, s[2:3] offset:2304
	v_add_u32_e32 v140, 0x8000, v140
	v_add_u32_e32 v141, 0x6a000, v141
	global_load_dwordx4 v[166:169], v140, s[52:53]
	global_load_dwordx4 v[170:173], v141, s[2:3] offset:2048
	global_load_dwordx4 v[174:177], v140, s[52:53] offset:256
	global_load_dwordx4 v[178:181], v141, s[2:3] offset:2304
	v_add_u32_e32 v140, 0x8000, v140
	v_add_u32_e32 v141, 0x6a000, v141
	global_load_dwordx4 v[182:185], v140, s[52:53]
	global_load_dwordx4 v[186:189], v141, s[2:3] offset:2048
	global_load_dwordx4 v[190:193], v140, s[52:53] offset:256
	global_load_dwordx4 v[194:197], v141, s[2:3] offset:2304
	v_add_u32_e32 v140, 0x8000, v140
	v_add_u32_e32 v141, 0x6a000, v141
	s_waitcnt vmcnt(12)
	v_pk_add_f32 v[126:127], v[126:127], v[224:225]
	v_pk_add_f32 v[128:129], v[128:129], v[226:227]
	v_pk_add_f32 v[122:123], v[122:123], v[228:229]
	v_pk_add_f32 v[124:125], v[124:125], v[230:231]
	v_pk_add_f32 v[118:119], v[118:119], v[232:233]
	v_pk_add_f32 v[120:121], v[120:121], v[234:235]
	v_pk_add_f32 v[114:115], v[114:115], v[236:237]
	v_pk_add_f32 v[116:117], v[116:117], v[238:239]
	v_pk_add_f32 v[110:111], v[110:111], v[224:225]
	v_pk_add_f32 v[112:113], v[112:113], v[226:227]
	v_pk_add_f32 v[106:107], v[106:107], v[228:229]
	v_pk_add_f32 v[108:109], v[108:109], v[230:231]
	v_pk_add_f32 v[102:103], v[102:103], v[232:233]
	v_pk_add_f32 v[104:105], v[104:105], v[234:235]
	v_pk_add_f32 v[98:99], v[98:99], v[236:237]
	v_pk_add_f32 v[100:101], v[100:101], v[238:239]
	v_pk_add_f32 v[94:95], v[94:95], v[224:225]
	v_pk_add_f32 v[96:97], v[96:97], v[226:227]
	v_pk_add_f32 v[90:91], v[90:91], v[228:229]
	v_pk_add_f32 v[92:93], v[92:93], v[230:231]
	v_pk_add_f32 v[86:87], v[86:87], v[232:233]
	v_pk_add_f32 v[88:89], v[88:89], v[234:235]
	v_pk_add_f32 v[82:83], v[82:83], v[236:237]
	v_pk_add_f32 v[84:85], v[84:85], v[238:239]
	v_pk_add_f32 v[78:79], v[78:79], v[224:225]
	v_pk_add_f32 v[80:81], v[80:81], v[226:227]
	v_pk_add_f32 v[74:75], v[74:75], v[228:229]
	v_pk_add_f32 v[76:77], v[76:77], v[230:231]
	v_pk_add_f32 v[70:71], v[70:71], v[232:233]
	v_pk_add_f32 v[72:73], v[72:73], v[234:235]
	v_pk_add_f32 v[66:67], v[66:67], v[236:237]
	v_pk_add_f32 v[68:69], v[68:69], v[238:239]
	v_pk_add_f32 v[62:63], v[62:63], v[224:225]
	v_pk_add_f32 v[64:65], v[64:65], v[226:227]
	v_pk_add_f32 v[58:59], v[58:59], v[228:229]
	v_pk_add_f32 v[60:61], v[60:61], v[230:231]
	v_pk_add_f32 v[54:55], v[54:55], v[232:233]
	v_pk_add_f32 v[56:57], v[56:57], v[234:235]
	v_pk_add_f32 v[50:51], v[50:51], v[236:237]
	v_pk_add_f32 v[52:53], v[52:53], v[238:239]
	v_pk_add_f32 v[46:47], v[46:47], v[224:225]
	v_pk_add_f32 v[48:49], v[48:49], v[226:227]
	v_pk_add_f32 v[42:43], v[42:43], v[228:229]
	v_pk_add_f32 v[44:45], v[44:45], v[230:231]
	v_pk_add_f32 v[38:39], v[38:39], v[232:233]
	v_pk_add_f32 v[40:41], v[40:41], v[234:235]
	v_pk_add_f32 v[34:35], v[34:35], v[236:237]
	v_pk_add_f32 v[36:37], v[36:37], v[238:239]
	v_pk_add_f32 v[30:31], v[30:31], v[224:225]
	v_pk_add_f32 v[32:33], v[32:33], v[226:227]
	v_pk_add_f32 v[26:27], v[26:27], v[228:229]
	v_pk_add_f32 v[28:29], v[28:29], v[230:231]
	v_pk_add_f32 v[22:23], v[22:23], v[232:233]
	v_pk_add_f32 v[24:25], v[24:25], v[234:235]
	v_pk_add_f32 v[18:19], v[18:19], v[236:237]
	v_pk_add_f32 v[20:21], v[20:21], v[238:239]
	v_pk_add_f32 v[14:15], v[14:15], v[224:225]
	v_pk_add_f32 v[16:17], v[16:17], v[226:227]
	v_pk_add_f32 v[10:11], v[10:11], v[228:229]
	v_pk_add_f32 v[12:13], v[12:13], v[230:231]
	v_pk_add_f32 v[6:7], v[6:7], v[232:233]
	v_pk_add_f32 v[8:9], v[8:9], v[234:235]
	v_pk_add_f32 v[2:3], v[2:3], v[236:237]
	v_pk_add_f32 v[4:5], v[4:5], v[238:239]
	global_load_dwordx4 v[224:227], v140, s[52:53]
	global_load_dwordx4 v[228:231], v141, s[2:3] offset:2048
	global_load_dwordx4 v[232:235], v140, s[52:53] offset:256
	global_load_dwordx4 v[236:239], v141, s[2:3] offset:2304
	v_add_u32_e32 v140, 0x28000, v140
	v_add_u32_e32 v141, 0x212000, v141
	s_waitcnt vmcnt(14)
	v_mul_f32_e32 v126, 0xbfb8aa3b, v126
	v_mul_f32_e32 v127, 0xbfb8aa3b, v127
	v_mul_f32_e32 v128, 0xbfb8aa3b, v128
	v_mul_f32_e32 v129, 0xbfb8aa3b, v129
	v_mul_f32_e32 v122, 0xbfb8aa3b, v122
	v_mul_f32_e32 v123, 0xbfb8aa3b, v123
	v_mul_f32_e32 v124, 0xbfb8aa3b, v124
	v_mul_f32_e32 v125, 0xbfb8aa3b, v125
	v_exp_f32_e32 v126, v126
	v_exp_f32_e32 v127, v127
	v_exp_f32_e32 v128, v128
	v_exp_f32_e32 v129, v129
	v_exp_f32_e32 v122, v122
	v_exp_f32_e32 v123, v123
	v_exp_f32_e32 v124, v124
	v_exp_f32_e32 v125, v125
	v_add_f32_e32 v126, 1.0, v126
	v_add_f32_e32 v127, 1.0, v127
	v_add_f32_e32 v128, 1.0, v128
	v_add_f32_e32 v129, 1.0, v129
	v_add_f32_e32 v122, 1.0, v122
	v_add_f32_e32 v123, 1.0, v123
	v_add_f32_e32 v124, 1.0, v124
	v_add_f32_e32 v125, 1.0, v125
	v_rcp_f32_e32 v126, v126
	v_rcp_f32_e32 v127, v127
	v_rcp_f32_e32 v128, v128
	v_rcp_f32_e32 v129, v129
	v_rcp_f32_e32 v122, v122
	v_rcp_f32_e32 v123, v123
	v_rcp_f32_e32 v124, v124
	v_rcp_f32_e32 v125, v125
	v_lshlrev_b32_e32 v143, 16, v150
	v_mul_f32_e32 v126, v126, v143
	v_lshlrev_b32_e32 v144, 16, v154
	v_mul_f32_e32 v126, v126, v144
	v_and_b32_e32 v143, 0xffff0000, v150
	v_mul_f32_e32 v127, v127, v143
	v_and_b32_e32 v144, 0xffff0000, v154
	v_mul_f32_e32 v127, v127, v144
	v_lshlrev_b32_e32 v143, 16, v151
	v_mul_f32_e32 v128, v128, v143
	v_lshlrev_b32_e32 v144, 16, v155
	v_mul_f32_e32 v128, v128, v144
	v_and_b32_e32 v143, 0xffff0000, v151
	v_mul_f32_e32 v129, v129, v143
	v_and_b32_e32 v144, 0xffff0000, v155
	v_mul_f32_e32 v129, v129, v144
	v_lshlrev_b32_e32 v143, 16, v152
	v_mul_f32_e32 v122, v122, v143
	v_lshlrev_b32_e32 v144, 16, v156
	v_mul_f32_e32 v122, v122, v144
	v_and_b32_e32 v143, 0xffff0000, v152
	v_mul_f32_e32 v123, v123, v143
	v_and_b32_e32 v144, 0xffff0000, v156
	v_mul_f32_e32 v123, v123, v144
	v_lshlrev_b32_e32 v143, 16, v153
	v_mul_f32_e32 v124, v124, v143
	v_lshlrev_b32_e32 v144, 16, v157
	v_mul_f32_e32 v124, v124, v144
	v_and_b32_e32 v143, 0xffff0000, v153
	v_mul_f32_e32 v125, v125, v143
	v_and_b32_e32 v144, 0xffff0000, v157
	v_mul_f32_e32 v125, v125, v144
	v_cvt_pk_bf16_f32 v150, v126, v127
	v_cvt_pk_bf16_f32 v151, v128, v129
	v_cvt_pk_bf16_f32 v152, v122, v123
	v_cvt_pk_bf16_f32 v153, v124, v125
	global_store_dwordx4 v142, v[150:153], s[16:17]
	s_nop 0
	global_load_dwordx4 v[150:153], v140, s[52:53]
	global_load_dwordx4 v[154:157], v141, s[2:3] offset:2048
	s_waitcnt vmcnt(15)
	v_mul_f32_e32 v118, 0xbfb8aa3b, v118
	v_mul_f32_e32 v119, 0xbfb8aa3b, v119
	v_mul_f32_e32 v120, 0xbfb8aa3b, v120
	v_mul_f32_e32 v121, 0xbfb8aa3b, v121
	v_mul_f32_e32 v114, 0xbfb8aa3b, v114
	v_mul_f32_e32 v115, 0xbfb8aa3b, v115
	v_mul_f32_e32 v116, 0xbfb8aa3b, v116
	v_mul_f32_e32 v117, 0xbfb8aa3b, v117
	v_exp_f32_e32 v118, v118
	v_exp_f32_e32 v119, v119
	v_exp_f32_e32 v120, v120
	v_exp_f32_e32 v121, v121
	v_exp_f32_e32 v114, v114
	v_exp_f32_e32 v115, v115
	v_exp_f32_e32 v116, v116
	v_exp_f32_e32 v117, v117
	v_add_f32_e32 v118, 1.0, v118
	v_add_f32_e32 v119, 1.0, v119
	v_add_f32_e32 v120, 1.0, v120
	v_add_f32_e32 v121, 1.0, v121
	v_add_f32_e32 v114, 1.0, v114
	v_add_f32_e32 v115, 1.0, v115
	v_add_f32_e32 v116, 1.0, v116
	v_add_f32_e32 v117, 1.0, v117
	v_rcp_f32_e32 v118, v118
	v_rcp_f32_e32 v119, v119
	v_rcp_f32_e32 v120, v120
	v_rcp_f32_e32 v121, v121
	v_rcp_f32_e32 v114, v114
	v_rcp_f32_e32 v115, v115
	v_rcp_f32_e32 v116, v116
	v_rcp_f32_e32 v117, v117
	v_lshlrev_b32_e32 v143, 16, v158
	v_mul_f32_e32 v118, v118, v143
	v_lshlrev_b32_e32 v144, 16, v162
	v_mul_f32_e32 v118, v118, v144
	v_and_b32_e32 v143, 0xffff0000, v158
	v_mul_f32_e32 v119, v119, v143
	v_and_b32_e32 v144, 0xffff0000, v162
	v_mul_f32_e32 v119, v119, v144
	v_lshlrev_b32_e32 v143, 16, v159
	v_mul_f32_e32 v120, v120, v143
	v_lshlrev_b32_e32 v144, 16, v163
	v_mul_f32_e32 v120, v120, v144
	v_and_b32_e32 v143, 0xffff0000, v159
	v_mul_f32_e32 v121, v121, v143
	v_and_b32_e32 v144, 0xffff0000, v163
	v_mul_f32_e32 v121, v121, v144
	v_lshlrev_b32_e32 v143, 16, v160
	v_mul_f32_e32 v114, v114, v143
	v_lshlrev_b32_e32 v144, 16, v164
	v_mul_f32_e32 v114, v114, v144
	v_and_b32_e32 v143, 0xffff0000, v160
	v_mul_f32_e32 v115, v115, v143
	v_and_b32_e32 v144, 0xffff0000, v164
	v_mul_f32_e32 v115, v115, v144
	v_lshlrev_b32_e32 v143, 16, v161
	v_mul_f32_e32 v116, v116, v143
	v_lshlrev_b32_e32 v144, 16, v165
	v_mul_f32_e32 v116, v116, v144
	v_and_b32_e32 v143, 0xffff0000, v161
	v_mul_f32_e32 v117, v117, v143
	v_and_b32_e32 v144, 0xffff0000, v165
	v_mul_f32_e32 v117, v117, v144
	v_cvt_pk_bf16_f32 v158, v118, v119
	v_cvt_pk_bf16_f32 v159, v120, v121
	v_cvt_pk_bf16_f32 v160, v114, v115
	v_cvt_pk_bf16_f32 v161, v116, v117
	global_store_dwordx4 v142, v[158:161], s[16:17] offset:256
	v_add_u32_e32 v142, 0x8000, v142
	global_load_dwordx4 v[158:161], v140, s[52:53] offset:256
	global_load_dwordx4 v[162:165], v141, s[2:3] offset:2304
	v_add_u32_e32 v140, 0x8000, v140
	v_add_u32_e32 v141, 0x6a000, v141
	s_waitcnt vmcnt(16)
	v_mul_f32_e32 v110, 0xbfb8aa3b, v110
	v_mul_f32_e32 v111, 0xbfb8aa3b, v111
	v_mul_f32_e32 v112, 0xbfb8aa3b, v112
	v_mul_f32_e32 v113, 0xbfb8aa3b, v113
	v_mul_f32_e32 v106, 0xbfb8aa3b, v106
	v_mul_f32_e32 v107, 0xbfb8aa3b, v107
	v_mul_f32_e32 v108, 0xbfb8aa3b, v108
	v_mul_f32_e32 v109, 0xbfb8aa3b, v109
	v_exp_f32_e32 v110, v110
	v_exp_f32_e32 v111, v111
	v_exp_f32_e32 v112, v112
	v_exp_f32_e32 v113, v113
	v_exp_f32_e32 v106, v106
	v_exp_f32_e32 v107, v107
	v_exp_f32_e32 v108, v108
	v_exp_f32_e32 v109, v109
	v_add_f32_e32 v110, 1.0, v110
	v_add_f32_e32 v111, 1.0, v111
	v_add_f32_e32 v112, 1.0, v112
	v_add_f32_e32 v113, 1.0, v113
	v_add_f32_e32 v106, 1.0, v106
	v_add_f32_e32 v107, 1.0, v107
	v_add_f32_e32 v108, 1.0, v108
	v_add_f32_e32 v109, 1.0, v109
	v_rcp_f32_e32 v110, v110
	v_rcp_f32_e32 v111, v111
	v_rcp_f32_e32 v112, v112
	v_rcp_f32_e32 v113, v113
	v_rcp_f32_e32 v106, v106
	v_rcp_f32_e32 v107, v107
	v_rcp_f32_e32 v108, v108
	v_rcp_f32_e32 v109, v109
	v_lshlrev_b32_e32 v143, 16, v166
	v_mul_f32_e32 v110, v110, v143
	v_lshlrev_b32_e32 v144, 16, v170
	v_mul_f32_e32 v110, v110, v144
	v_and_b32_e32 v143, 0xffff0000, v166
	v_mul_f32_e32 v111, v111, v143
	v_and_b32_e32 v144, 0xffff0000, v170
	v_mul_f32_e32 v111, v111, v144
	v_lshlrev_b32_e32 v143, 16, v167
	v_mul_f32_e32 v112, v112, v143
	v_lshlrev_b32_e32 v144, 16, v171
	v_mul_f32_e32 v112, v112, v144
	v_and_b32_e32 v143, 0xffff0000, v167
	v_mul_f32_e32 v113, v113, v143
	v_and_b32_e32 v144, 0xffff0000, v171
	v_mul_f32_e32 v113, v113, v144
	v_lshlrev_b32_e32 v143, 16, v168
	v_mul_f32_e32 v106, v106, v143
	v_lshlrev_b32_e32 v144, 16, v172
	v_mul_f32_e32 v106, v106, v144
	v_and_b32_e32 v143, 0xffff0000, v168
	v_mul_f32_e32 v107, v107, v143
	v_and_b32_e32 v144, 0xffff0000, v172
	v_mul_f32_e32 v107, v107, v144
	v_lshlrev_b32_e32 v143, 16, v169
	v_mul_f32_e32 v108, v108, v143
	v_lshlrev_b32_e32 v144, 16, v173
	v_mul_f32_e32 v108, v108, v144
	v_and_b32_e32 v143, 0xffff0000, v169
	v_mul_f32_e32 v109, v109, v143
	v_and_b32_e32 v144, 0xffff0000, v173
	v_mul_f32_e32 v109, v109, v144
	v_cvt_pk_bf16_f32 v166, v110, v111
	v_cvt_pk_bf16_f32 v167, v112, v113
	v_cvt_pk_bf16_f32 v168, v106, v107
	v_cvt_pk_bf16_f32 v169, v108, v109
	global_store_dwordx4 v142, v[166:169], s[16:17]
	s_nop 0
	global_load_dwordx4 v[166:169], v140, s[52:53]
	global_load_dwordx4 v[170:173], v141, s[2:3] offset:2048
	s_waitcnt vmcnt(17)
	v_mul_f32_e32 v102, 0xbfb8aa3b, v102
	v_mul_f32_e32 v103, 0xbfb8aa3b, v103
	v_mul_f32_e32 v104, 0xbfb8aa3b, v104
	v_mul_f32_e32 v105, 0xbfb8aa3b, v105
	v_mul_f32_e32 v98, 0xbfb8aa3b, v98
	v_mul_f32_e32 v99, 0xbfb8aa3b, v99
	v_mul_f32_e32 v100, 0xbfb8aa3b, v100
	v_mul_f32_e32 v101, 0xbfb8aa3b, v101
	v_exp_f32_e32 v102, v102
	v_exp_f32_e32 v103, v103
	v_exp_f32_e32 v104, v104
	v_exp_f32_e32 v105, v105
	v_exp_f32_e32 v98, v98
	v_exp_f32_e32 v99, v99
	v_exp_f32_e32 v100, v100
	v_exp_f32_e32 v101, v101
	v_add_f32_e32 v102, 1.0, v102
	v_add_f32_e32 v103, 1.0, v103
	v_add_f32_e32 v104, 1.0, v104
	v_add_f32_e32 v105, 1.0, v105
	v_add_f32_e32 v98, 1.0, v98
	v_add_f32_e32 v99, 1.0, v99
	v_add_f32_e32 v100, 1.0, v100
	v_add_f32_e32 v101, 1.0, v101
	v_rcp_f32_e32 v102, v102
	v_rcp_f32_e32 v103, v103
	v_rcp_f32_e32 v104, v104
	v_rcp_f32_e32 v105, v105
	v_rcp_f32_e32 v98, v98
	v_rcp_f32_e32 v99, v99
	v_rcp_f32_e32 v100, v100
	v_rcp_f32_e32 v101, v101
	v_lshlrev_b32_e32 v143, 16, v174
	v_mul_f32_e32 v102, v102, v143
	v_lshlrev_b32_e32 v144, 16, v178
	v_mul_f32_e32 v102, v102, v144
	v_and_b32_e32 v143, 0xffff0000, v174
	v_mul_f32_e32 v103, v103, v143
	v_and_b32_e32 v144, 0xffff0000, v178
	v_mul_f32_e32 v103, v103, v144
	v_lshlrev_b32_e32 v143, 16, v175
	v_mul_f32_e32 v104, v104, v143
	v_lshlrev_b32_e32 v144, 16, v179
	v_mul_f32_e32 v104, v104, v144
	v_and_b32_e32 v143, 0xffff0000, v175
	v_mul_f32_e32 v105, v105, v143
	v_and_b32_e32 v144, 0xffff0000, v179
	v_mul_f32_e32 v105, v105, v144
	v_lshlrev_b32_e32 v143, 16, v176
	v_mul_f32_e32 v98, v98, v143
	v_lshlrev_b32_e32 v144, 16, v180
	v_mul_f32_e32 v98, v98, v144
	v_and_b32_e32 v143, 0xffff0000, v176
	v_mul_f32_e32 v99, v99, v143
	v_and_b32_e32 v144, 0xffff0000, v180
	v_mul_f32_e32 v99, v99, v144
	v_lshlrev_b32_e32 v143, 16, v177
	v_mul_f32_e32 v100, v100, v143
	v_lshlrev_b32_e32 v144, 16, v181
	v_mul_f32_e32 v100, v100, v144
	v_and_b32_e32 v143, 0xffff0000, v177
	v_mul_f32_e32 v101, v101, v143
	v_and_b32_e32 v144, 0xffff0000, v181
	v_mul_f32_e32 v101, v101, v144
	v_cvt_pk_bf16_f32 v174, v102, v103
	v_cvt_pk_bf16_f32 v175, v104, v105
	v_cvt_pk_bf16_f32 v176, v98, v99
	v_cvt_pk_bf16_f32 v177, v100, v101
	global_store_dwordx4 v142, v[174:177], s[16:17] offset:256
	v_add_u32_e32 v142, 0x8000, v142
	global_load_dwordx4 v[174:177], v140, s[52:53] offset:256
	global_load_dwordx4 v[178:181], v141, s[2:3] offset:2304
	v_add_u32_e32 v140, 0x8000, v140
	v_add_u32_e32 v141, 0x6a000, v141
	s_waitcnt vmcnt(18)
	v_mul_f32_e32 v94, 0xbfb8aa3b, v94
	v_mul_f32_e32 v95, 0xbfb8aa3b, v95
	v_mul_f32_e32 v96, 0xbfb8aa3b, v96
	v_mul_f32_e32 v97, 0xbfb8aa3b, v97
	v_mul_f32_e32 v90, 0xbfb8aa3b, v90
	v_mul_f32_e32 v91, 0xbfb8aa3b, v91
	v_mul_f32_e32 v92, 0xbfb8aa3b, v92
	v_mul_f32_e32 v93, 0xbfb8aa3b, v93
	v_exp_f32_e32 v94, v94
	v_exp_f32_e32 v95, v95
	v_exp_f32_e32 v96, v96
	v_exp_f32_e32 v97, v97
	v_exp_f32_e32 v90, v90
	v_exp_f32_e32 v91, v91
	v_exp_f32_e32 v92, v92
	v_exp_f32_e32 v93, v93
	v_add_f32_e32 v94, 1.0, v94
	v_add_f32_e32 v95, 1.0, v95
	v_add_f32_e32 v96, 1.0, v96
	v_add_f32_e32 v97, 1.0, v97
	v_add_f32_e32 v90, 1.0, v90
	v_add_f32_e32 v91, 1.0, v91
	v_add_f32_e32 v92, 1.0, v92
	v_add_f32_e32 v93, 1.0, v93
	v_rcp_f32_e32 v94, v94
	v_rcp_f32_e32 v95, v95
	v_rcp_f32_e32 v96, v96
	v_rcp_f32_e32 v97, v97
	v_rcp_f32_e32 v90, v90
	v_rcp_f32_e32 v91, v91
	v_rcp_f32_e32 v92, v92
	v_rcp_f32_e32 v93, v93
	v_lshlrev_b32_e32 v143, 16, v182
	v_mul_f32_e32 v94, v94, v143
	v_lshlrev_b32_e32 v144, 16, v186
	v_mul_f32_e32 v94, v94, v144
	v_and_b32_e32 v143, 0xffff0000, v182
	v_mul_f32_e32 v95, v95, v143
	v_and_b32_e32 v144, 0xffff0000, v186
	v_mul_f32_e32 v95, v95, v144
	v_lshlrev_b32_e32 v143, 16, v183
	v_mul_f32_e32 v96, v96, v143
	v_lshlrev_b32_e32 v144, 16, v187
	v_mul_f32_e32 v96, v96, v144
	v_and_b32_e32 v143, 0xffff0000, v183
	v_mul_f32_e32 v97, v97, v143
	v_and_b32_e32 v144, 0xffff0000, v187
	v_mul_f32_e32 v97, v97, v144
	v_lshlrev_b32_e32 v143, 16, v184
	v_mul_f32_e32 v90, v90, v143
	v_lshlrev_b32_e32 v144, 16, v188
	v_mul_f32_e32 v90, v90, v144
	v_and_b32_e32 v143, 0xffff0000, v184
	v_mul_f32_e32 v91, v91, v143
	v_and_b32_e32 v144, 0xffff0000, v188
	v_mul_f32_e32 v91, v91, v144
	v_lshlrev_b32_e32 v143, 16, v185
	v_mul_f32_e32 v92, v92, v143
	v_lshlrev_b32_e32 v144, 16, v189
	v_mul_f32_e32 v92, v92, v144
	v_and_b32_e32 v143, 0xffff0000, v185
	v_mul_f32_e32 v93, v93, v143
	v_and_b32_e32 v144, 0xffff0000, v189
	v_mul_f32_e32 v93, v93, v144
	v_cvt_pk_bf16_f32 v182, v94, v95
	v_cvt_pk_bf16_f32 v183, v96, v97
	v_cvt_pk_bf16_f32 v184, v90, v91
	v_cvt_pk_bf16_f32 v185, v92, v93
	global_store_dwordx4 v142, v[182:185], s[16:17]
	s_nop 0
	global_load_dwordx4 v[182:185], v140, s[52:53]
	global_load_dwordx4 v[186:189], v141, s[2:3] offset:2048
	s_waitcnt vmcnt(19)
	v_mul_f32_e32 v86, 0xbfb8aa3b, v86
	v_mul_f32_e32 v87, 0xbfb8aa3b, v87
	v_mul_f32_e32 v88, 0xbfb8aa3b, v88
	v_mul_f32_e32 v89, 0xbfb8aa3b, v89
	v_mul_f32_e32 v82, 0xbfb8aa3b, v82
	v_mul_f32_e32 v83, 0xbfb8aa3b, v83
	v_mul_f32_e32 v84, 0xbfb8aa3b, v84
	v_mul_f32_e32 v85, 0xbfb8aa3b, v85
	v_exp_f32_e32 v86, v86
	v_exp_f32_e32 v87, v87
	v_exp_f32_e32 v88, v88
	v_exp_f32_e32 v89, v89
	v_exp_f32_e32 v82, v82
	v_exp_f32_e32 v83, v83
	v_exp_f32_e32 v84, v84
	v_exp_f32_e32 v85, v85
	v_add_f32_e32 v86, 1.0, v86
	v_add_f32_e32 v87, 1.0, v87
	v_add_f32_e32 v88, 1.0, v88
	v_add_f32_e32 v89, 1.0, v89
	v_add_f32_e32 v82, 1.0, v82
	v_add_f32_e32 v83, 1.0, v83
	v_add_f32_e32 v84, 1.0, v84
	v_add_f32_e32 v85, 1.0, v85
	v_rcp_f32_e32 v86, v86
	v_rcp_f32_e32 v87, v87
	v_rcp_f32_e32 v88, v88
	v_rcp_f32_e32 v89, v89
	v_rcp_f32_e32 v82, v82
	v_rcp_f32_e32 v83, v83
	v_rcp_f32_e32 v84, v84
	v_rcp_f32_e32 v85, v85
	v_lshlrev_b32_e32 v143, 16, v190
	v_mul_f32_e32 v86, v86, v143
	v_lshlrev_b32_e32 v144, 16, v194
	v_mul_f32_e32 v86, v86, v144
	v_and_b32_e32 v143, 0xffff0000, v190
	v_mul_f32_e32 v87, v87, v143
	v_and_b32_e32 v144, 0xffff0000, v194
	v_mul_f32_e32 v87, v87, v144
	v_lshlrev_b32_e32 v143, 16, v191
	v_mul_f32_e32 v88, v88, v143
	v_lshlrev_b32_e32 v144, 16, v195
	v_mul_f32_e32 v88, v88, v144
	v_and_b32_e32 v143, 0xffff0000, v191
	v_mul_f32_e32 v89, v89, v143
	v_and_b32_e32 v144, 0xffff0000, v195
	v_mul_f32_e32 v89, v89, v144
	v_lshlrev_b32_e32 v143, 16, v192
	v_mul_f32_e32 v82, v82, v143
	v_lshlrev_b32_e32 v144, 16, v196
	v_mul_f32_e32 v82, v82, v144
	v_and_b32_e32 v143, 0xffff0000, v192
	v_mul_f32_e32 v83, v83, v143
	v_and_b32_e32 v144, 0xffff0000, v196
	v_mul_f32_e32 v83, v83, v144
	v_lshlrev_b32_e32 v143, 16, v193
	v_mul_f32_e32 v84, v84, v143
	v_lshlrev_b32_e32 v144, 16, v197
	v_mul_f32_e32 v84, v84, v144
	v_and_b32_e32 v143, 0xffff0000, v193
	v_mul_f32_e32 v85, v85, v143
	v_and_b32_e32 v144, 0xffff0000, v197
	v_mul_f32_e32 v85, v85, v144
	v_cvt_pk_bf16_f32 v190, v86, v87
	v_cvt_pk_bf16_f32 v191, v88, v89
	v_cvt_pk_bf16_f32 v192, v82, v83
	v_cvt_pk_bf16_f32 v193, v84, v85
	global_store_dwordx4 v142, v[190:193], s[16:17] offset:256
	v_add_u32_e32 v142, 0x8000, v142
	global_load_dwordx4 v[190:193], v140, s[52:53] offset:256
	global_load_dwordx4 v[194:197], v141, s[2:3] offset:2304
	v_add_u32_e32 v140, 0x8000, v140
	v_add_u32_e32 v141, 0x6a000, v141
	s_waitcnt vmcnt(20)
	v_mul_f32_e32 v78, 0xbfb8aa3b, v78
	v_mul_f32_e32 v79, 0xbfb8aa3b, v79
	v_mul_f32_e32 v80, 0xbfb8aa3b, v80
	v_mul_f32_e32 v81, 0xbfb8aa3b, v81
	v_mul_f32_e32 v74, 0xbfb8aa3b, v74
	v_mul_f32_e32 v75, 0xbfb8aa3b, v75
	v_mul_f32_e32 v76, 0xbfb8aa3b, v76
	v_mul_f32_e32 v77, 0xbfb8aa3b, v77
	v_exp_f32_e32 v78, v78
	v_exp_f32_e32 v79, v79
	v_exp_f32_e32 v80, v80
	v_exp_f32_e32 v81, v81
	v_exp_f32_e32 v74, v74
	v_exp_f32_e32 v75, v75
	v_exp_f32_e32 v76, v76
	v_exp_f32_e32 v77, v77
	v_add_f32_e32 v78, 1.0, v78
	v_add_f32_e32 v79, 1.0, v79
	v_add_f32_e32 v80, 1.0, v80
	v_add_f32_e32 v81, 1.0, v81
	v_add_f32_e32 v74, 1.0, v74
	v_add_f32_e32 v75, 1.0, v75
	v_add_f32_e32 v76, 1.0, v76
	v_add_f32_e32 v77, 1.0, v77
	v_rcp_f32_e32 v78, v78
	v_rcp_f32_e32 v79, v79
	v_rcp_f32_e32 v80, v80
	v_rcp_f32_e32 v81, v81
	v_rcp_f32_e32 v74, v74
	v_rcp_f32_e32 v75, v75
	v_rcp_f32_e32 v76, v76
	v_rcp_f32_e32 v77, v77
	v_lshlrev_b32_e32 v143, 16, v224
	v_mul_f32_e32 v78, v78, v143
	v_lshlrev_b32_e32 v144, 16, v228
	v_mul_f32_e32 v78, v78, v144
	v_and_b32_e32 v143, 0xffff0000, v224
	v_mul_f32_e32 v79, v79, v143
	v_and_b32_e32 v144, 0xffff0000, v228
	v_mul_f32_e32 v79, v79, v144
	v_lshlrev_b32_e32 v143, 16, v225
	v_mul_f32_e32 v80, v80, v143
	v_lshlrev_b32_e32 v144, 16, v229
	v_mul_f32_e32 v80, v80, v144
	v_and_b32_e32 v143, 0xffff0000, v225
	v_mul_f32_e32 v81, v81, v143
	v_and_b32_e32 v144, 0xffff0000, v229
	v_mul_f32_e32 v81, v81, v144
	v_lshlrev_b32_e32 v143, 16, v226
	v_mul_f32_e32 v74, v74, v143
	v_lshlrev_b32_e32 v144, 16, v230
	v_mul_f32_e32 v74, v74, v144
	v_and_b32_e32 v143, 0xffff0000, v226
	v_mul_f32_e32 v75, v75, v143
	v_and_b32_e32 v144, 0xffff0000, v230
	v_mul_f32_e32 v75, v75, v144
	v_lshlrev_b32_e32 v143, 16, v227
	v_mul_f32_e32 v76, v76, v143
	v_lshlrev_b32_e32 v144, 16, v231
	v_mul_f32_e32 v76, v76, v144
	v_and_b32_e32 v143, 0xffff0000, v227
	v_mul_f32_e32 v77, v77, v143
	v_and_b32_e32 v144, 0xffff0000, v231
	v_mul_f32_e32 v77, v77, v144
	v_cvt_pk_bf16_f32 v224, v78, v79
	v_cvt_pk_bf16_f32 v225, v80, v81
	v_cvt_pk_bf16_f32 v226, v74, v75
	v_cvt_pk_bf16_f32 v227, v76, v77
	global_store_dwordx4 v142, v[224:227], s[16:17]
	s_nop 0
	global_load_dwordx4 v[224:227], v140, s[52:53]
	global_load_dwordx4 v[228:231], v141, s[2:3] offset:2048
	s_waitcnt vmcnt(21)
	v_mul_f32_e32 v70, 0xbfb8aa3b, v70
	v_mul_f32_e32 v71, 0xbfb8aa3b, v71
	v_mul_f32_e32 v72, 0xbfb8aa3b, v72
	v_mul_f32_e32 v73, 0xbfb8aa3b, v73
	v_mul_f32_e32 v66, 0xbfb8aa3b, v66
	v_mul_f32_e32 v67, 0xbfb8aa3b, v67
	v_mul_f32_e32 v68, 0xbfb8aa3b, v68
	v_mul_f32_e32 v69, 0xbfb8aa3b, v69
	v_exp_f32_e32 v70, v70
	v_exp_f32_e32 v71, v71
	v_exp_f32_e32 v72, v72
	v_exp_f32_e32 v73, v73
	v_exp_f32_e32 v66, v66
	v_exp_f32_e32 v67, v67
	v_exp_f32_e32 v68, v68
	v_exp_f32_e32 v69, v69
	v_add_f32_e32 v70, 1.0, v70
	v_add_f32_e32 v71, 1.0, v71
	v_add_f32_e32 v72, 1.0, v72
	v_add_f32_e32 v73, 1.0, v73
	v_add_f32_e32 v66, 1.0, v66
	v_add_f32_e32 v67, 1.0, v67
	v_add_f32_e32 v68, 1.0, v68
	v_add_f32_e32 v69, 1.0, v69
	v_rcp_f32_e32 v70, v70
	v_rcp_f32_e32 v71, v71
	v_rcp_f32_e32 v72, v72
	v_rcp_f32_e32 v73, v73
	v_rcp_f32_e32 v66, v66
	v_rcp_f32_e32 v67, v67
	v_rcp_f32_e32 v68, v68
	v_rcp_f32_e32 v69, v69
	v_lshlrev_b32_e32 v143, 16, v232
	v_mul_f32_e32 v70, v70, v143
	v_lshlrev_b32_e32 v144, 16, v236
	v_mul_f32_e32 v70, v70, v144
	v_and_b32_e32 v143, 0xffff0000, v232
	v_mul_f32_e32 v71, v71, v143
	v_and_b32_e32 v144, 0xffff0000, v236
	v_mul_f32_e32 v71, v71, v144
	v_lshlrev_b32_e32 v143, 16, v233
	v_mul_f32_e32 v72, v72, v143
	v_lshlrev_b32_e32 v144, 16, v237
	v_mul_f32_e32 v72, v72, v144
	v_and_b32_e32 v143, 0xffff0000, v233
	v_mul_f32_e32 v73, v73, v143
	v_and_b32_e32 v144, 0xffff0000, v237
	v_mul_f32_e32 v73, v73, v144
	v_lshlrev_b32_e32 v143, 16, v234
	v_mul_f32_e32 v66, v66, v143
	v_lshlrev_b32_e32 v144, 16, v238
	v_mul_f32_e32 v66, v66, v144
	v_and_b32_e32 v143, 0xffff0000, v234
	v_mul_f32_e32 v67, v67, v143
	v_and_b32_e32 v144, 0xffff0000, v238
	v_mul_f32_e32 v67, v67, v144
	v_lshlrev_b32_e32 v143, 16, v235
	v_mul_f32_e32 v68, v68, v143
	v_lshlrev_b32_e32 v144, 16, v239
	v_mul_f32_e32 v68, v68, v144
	v_and_b32_e32 v143, 0xffff0000, v235
	v_mul_f32_e32 v69, v69, v143
	v_and_b32_e32 v144, 0xffff0000, v239
	v_mul_f32_e32 v69, v69, v144
	v_cvt_pk_bf16_f32 v232, v70, v71
	v_cvt_pk_bf16_f32 v233, v72, v73
	v_cvt_pk_bf16_f32 v234, v66, v67
	v_cvt_pk_bf16_f32 v235, v68, v69
	global_store_dwordx4 v142, v[232:235], s[16:17] offset:256
	v_add_u32_e32 v142, 0x28000, v142
	global_load_dwordx4 v[232:235], v140, s[52:53] offset:256
	global_load_dwordx4 v[236:239], v141, s[2:3] offset:2304
	s_waitcnt vmcnt(21)
	v_mul_f32_e32 v62, 0xbfb8aa3b, v62
	v_mul_f32_e32 v63, 0xbfb8aa3b, v63
	v_mul_f32_e32 v64, 0xbfb8aa3b, v64
	v_mul_f32_e32 v65, 0xbfb8aa3b, v65
	v_mul_f32_e32 v58, 0xbfb8aa3b, v58
	v_mul_f32_e32 v59, 0xbfb8aa3b, v59
	v_mul_f32_e32 v60, 0xbfb8aa3b, v60
	v_mul_f32_e32 v61, 0xbfb8aa3b, v61
	v_exp_f32_e32 v62, v62
	v_exp_f32_e32 v63, v63
	v_exp_f32_e32 v64, v64
	v_exp_f32_e32 v65, v65
	v_exp_f32_e32 v58, v58
	v_exp_f32_e32 v59, v59
	v_exp_f32_e32 v60, v60
	v_exp_f32_e32 v61, v61
	v_add_f32_e32 v62, 1.0, v62
	v_add_f32_e32 v63, 1.0, v63
	v_add_f32_e32 v64, 1.0, v64
	v_add_f32_e32 v65, 1.0, v65
	v_add_f32_e32 v58, 1.0, v58
	v_add_f32_e32 v59, 1.0, v59
	v_add_f32_e32 v60, 1.0, v60
	v_add_f32_e32 v61, 1.0, v61
	v_rcp_f32_e32 v62, v62
	v_rcp_f32_e32 v63, v63
	v_rcp_f32_e32 v64, v64
	v_rcp_f32_e32 v65, v65
	v_rcp_f32_e32 v58, v58
	v_rcp_f32_e32 v59, v59
	v_rcp_f32_e32 v60, v60
	v_rcp_f32_e32 v61, v61
	v_lshlrev_b32_e32 v143, 16, v150
	v_mul_f32_e32 v62, v62, v143
	v_lshlrev_b32_e32 v144, 16, v154
	v_mul_f32_e32 v62, v62, v144
	v_and_b32_e32 v143, 0xffff0000, v150
	v_mul_f32_e32 v63, v63, v143
	v_and_b32_e32 v144, 0xffff0000, v154
	v_mul_f32_e32 v63, v63, v144
	v_lshlrev_b32_e32 v143, 16, v151
	v_mul_f32_e32 v64, v64, v143
	v_lshlrev_b32_e32 v144, 16, v155
	v_mul_f32_e32 v64, v64, v144
	v_and_b32_e32 v143, 0xffff0000, v151
	v_mul_f32_e32 v65, v65, v143
	v_and_b32_e32 v144, 0xffff0000, v155
	v_mul_f32_e32 v65, v65, v144
	v_lshlrev_b32_e32 v143, 16, v152
	v_mul_f32_e32 v58, v58, v143
	v_lshlrev_b32_e32 v144, 16, v156
	v_mul_f32_e32 v58, v58, v144
	v_and_b32_e32 v143, 0xffff0000, v152
	v_mul_f32_e32 v59, v59, v143
	v_and_b32_e32 v144, 0xffff0000, v156
	v_mul_f32_e32 v59, v59, v144
	v_lshlrev_b32_e32 v143, 16, v153
	v_mul_f32_e32 v60, v60, v143
	v_lshlrev_b32_e32 v144, 16, v157
	v_mul_f32_e32 v60, v60, v144
	v_and_b32_e32 v143, 0xffff0000, v153
	v_mul_f32_e32 v61, v61, v143
	v_and_b32_e32 v144, 0xffff0000, v157
	v_mul_f32_e32 v61, v61, v144
	v_cvt_pk_bf16_f32 v150, v62, v63
	v_cvt_pk_bf16_f32 v151, v64, v65
	v_cvt_pk_bf16_f32 v152, v58, v59
	v_cvt_pk_bf16_f32 v153, v60, v61
	global_store_dwordx4 v142, v[150:153], s[16:17]
	s_nop 0
	s_waitcnt vmcnt(19)
	v_mul_f32_e32 v54, 0xbfb8aa3b, v54
	v_mul_f32_e32 v55, 0xbfb8aa3b, v55
	v_mul_f32_e32 v56, 0xbfb8aa3b, v56
	v_mul_f32_e32 v57, 0xbfb8aa3b, v57
	v_mul_f32_e32 v50, 0xbfb8aa3b, v50
	v_mul_f32_e32 v51, 0xbfb8aa3b, v51
	v_mul_f32_e32 v52, 0xbfb8aa3b, v52
	v_mul_f32_e32 v53, 0xbfb8aa3b, v53
	v_exp_f32_e32 v54, v54
	v_exp_f32_e32 v55, v55
	v_exp_f32_e32 v56, v56
	v_exp_f32_e32 v57, v57
	v_exp_f32_e32 v50, v50
	v_exp_f32_e32 v51, v51
	v_exp_f32_e32 v52, v52
	v_exp_f32_e32 v53, v53
	v_add_f32_e32 v54, 1.0, v54
	v_add_f32_e32 v55, 1.0, v55
	v_add_f32_e32 v56, 1.0, v56
	v_add_f32_e32 v57, 1.0, v57
	v_add_f32_e32 v50, 1.0, v50
	v_add_f32_e32 v51, 1.0, v51
	v_add_f32_e32 v52, 1.0, v52
	v_add_f32_e32 v53, 1.0, v53
	v_rcp_f32_e32 v54, v54
	v_rcp_f32_e32 v55, v55
	v_rcp_f32_e32 v56, v56
	v_rcp_f32_e32 v57, v57
	v_rcp_f32_e32 v50, v50
	v_rcp_f32_e32 v51, v51
	v_rcp_f32_e32 v52, v52
	v_rcp_f32_e32 v53, v53
	v_lshlrev_b32_e32 v143, 16, v158
	v_mul_f32_e32 v54, v54, v143
	v_lshlrev_b32_e32 v144, 16, v162
	v_mul_f32_e32 v54, v54, v144
	v_and_b32_e32 v143, 0xffff0000, v158
	v_mul_f32_e32 v55, v55, v143
	v_and_b32_e32 v144, 0xffff0000, v162
	v_mul_f32_e32 v55, v55, v144
	v_lshlrev_b32_e32 v143, 16, v159
	v_mul_f32_e32 v56, v56, v143
	v_lshlrev_b32_e32 v144, 16, v163
	v_mul_f32_e32 v56, v56, v144
	v_and_b32_e32 v143, 0xffff0000, v159
	v_mul_f32_e32 v57, v57, v143
	v_and_b32_e32 v144, 0xffff0000, v163
	v_mul_f32_e32 v57, v57, v144
	v_lshlrev_b32_e32 v143, 16, v160
	v_mul_f32_e32 v50, v50, v143
	v_lshlrev_b32_e32 v144, 16, v164
	v_mul_f32_e32 v50, v50, v144
	v_and_b32_e32 v143, 0xffff0000, v160
	v_mul_f32_e32 v51, v51, v143
	v_and_b32_e32 v144, 0xffff0000, v164
	v_mul_f32_e32 v51, v51, v144
	v_lshlrev_b32_e32 v143, 16, v161
	v_mul_f32_e32 v52, v52, v143
	v_lshlrev_b32_e32 v144, 16, v165
	v_mul_f32_e32 v52, v52, v144
	v_and_b32_e32 v143, 0xffff0000, v161
	v_mul_f32_e32 v53, v53, v143
	v_and_b32_e32 v144, 0xffff0000, v165
	v_mul_f32_e32 v53, v53, v144
	v_cvt_pk_bf16_f32 v158, v54, v55
	v_cvt_pk_bf16_f32 v159, v56, v57
	v_cvt_pk_bf16_f32 v160, v50, v51
	v_cvt_pk_bf16_f32 v161, v52, v53
	global_store_dwordx4 v142, v[158:161], s[16:17] offset:256
	v_add_u32_e32 v142, 0x8000, v142
	s_waitcnt vmcnt(17)
	v_mul_f32_e32 v46, 0xbfb8aa3b, v46
	v_mul_f32_e32 v47, 0xbfb8aa3b, v47
	v_mul_f32_e32 v48, 0xbfb8aa3b, v48
	v_mul_f32_e32 v49, 0xbfb8aa3b, v49
	v_mul_f32_e32 v42, 0xbfb8aa3b, v42
	v_mul_f32_e32 v43, 0xbfb8aa3b, v43
	v_mul_f32_e32 v44, 0xbfb8aa3b, v44
	v_mul_f32_e32 v45, 0xbfb8aa3b, v45
	v_exp_f32_e32 v46, v46
	v_exp_f32_e32 v47, v47
	v_exp_f32_e32 v48, v48
	v_exp_f32_e32 v49, v49
	v_exp_f32_e32 v42, v42
	v_exp_f32_e32 v43, v43
	v_exp_f32_e32 v44, v44
	v_exp_f32_e32 v45, v45
	v_add_f32_e32 v46, 1.0, v46
	v_add_f32_e32 v47, 1.0, v47
	v_add_f32_e32 v48, 1.0, v48
	v_add_f32_e32 v49, 1.0, v49
	v_add_f32_e32 v42, 1.0, v42
	v_add_f32_e32 v43, 1.0, v43
	v_add_f32_e32 v44, 1.0, v44
	v_add_f32_e32 v45, 1.0, v45
	v_rcp_f32_e32 v46, v46
	v_rcp_f32_e32 v47, v47
	v_rcp_f32_e32 v48, v48
	v_rcp_f32_e32 v49, v49
	v_rcp_f32_e32 v42, v42
	v_rcp_f32_e32 v43, v43
	v_rcp_f32_e32 v44, v44
	v_rcp_f32_e32 v45, v45
	v_lshlrev_b32_e32 v143, 16, v166
	v_mul_f32_e32 v46, v46, v143
	v_lshlrev_b32_e32 v144, 16, v170
	v_mul_f32_e32 v46, v46, v144
	v_and_b32_e32 v143, 0xffff0000, v166
	v_mul_f32_e32 v47, v47, v143
	v_and_b32_e32 v144, 0xffff0000, v170
	v_mul_f32_e32 v47, v47, v144
	v_lshlrev_b32_e32 v143, 16, v167
	v_mul_f32_e32 v48, v48, v143
	v_lshlrev_b32_e32 v144, 16, v171
	v_mul_f32_e32 v48, v48, v144
	v_and_b32_e32 v143, 0xffff0000, v167
	v_mul_f32_e32 v49, v49, v143
	v_and_b32_e32 v144, 0xffff0000, v171
	v_mul_f32_e32 v49, v49, v144
	v_lshlrev_b32_e32 v143, 16, v168
	v_mul_f32_e32 v42, v42, v143
	v_lshlrev_b32_e32 v144, 16, v172
	v_mul_f32_e32 v42, v42, v144
	v_and_b32_e32 v143, 0xffff0000, v168
	v_mul_f32_e32 v43, v43, v143
	v_and_b32_e32 v144, 0xffff0000, v172
	v_mul_f32_e32 v43, v43, v144
	v_lshlrev_b32_e32 v143, 16, v169
	v_mul_f32_e32 v44, v44, v143
	v_lshlrev_b32_e32 v144, 16, v173
	v_mul_f32_e32 v44, v44, v144
	v_and_b32_e32 v143, 0xffff0000, v169
	v_mul_f32_e32 v45, v45, v143
	v_and_b32_e32 v144, 0xffff0000, v173
	v_mul_f32_e32 v45, v45, v144
	v_cvt_pk_bf16_f32 v166, v46, v47
	v_cvt_pk_bf16_f32 v167, v48, v49
	v_cvt_pk_bf16_f32 v168, v42, v43
	v_cvt_pk_bf16_f32 v169, v44, v45
	global_store_dwordx4 v142, v[166:169], s[16:17]
	s_nop 0
	s_waitcnt vmcnt(15)
	v_mul_f32_e32 v38, 0xbfb8aa3b, v38
	v_mul_f32_e32 v39, 0xbfb8aa3b, v39
	v_mul_f32_e32 v40, 0xbfb8aa3b, v40
	v_mul_f32_e32 v41, 0xbfb8aa3b, v41
	v_mul_f32_e32 v34, 0xbfb8aa3b, v34
	v_mul_f32_e32 v35, 0xbfb8aa3b, v35
	v_mul_f32_e32 v36, 0xbfb8aa3b, v36
	v_mul_f32_e32 v37, 0xbfb8aa3b, v37
	v_exp_f32_e32 v38, v38
	v_exp_f32_e32 v39, v39
	v_exp_f32_e32 v40, v40
	v_exp_f32_e32 v41, v41
	v_exp_f32_e32 v34, v34
	v_exp_f32_e32 v35, v35
	v_exp_f32_e32 v36, v36
	v_exp_f32_e32 v37, v37
	v_add_f32_e32 v38, 1.0, v38
	v_add_f32_e32 v39, 1.0, v39
	v_add_f32_e32 v40, 1.0, v40
	v_add_f32_e32 v41, 1.0, v41
	v_add_f32_e32 v34, 1.0, v34
	v_add_f32_e32 v35, 1.0, v35
	v_add_f32_e32 v36, 1.0, v36
	v_add_f32_e32 v37, 1.0, v37
	v_rcp_f32_e32 v38, v38
	v_rcp_f32_e32 v39, v39
	v_rcp_f32_e32 v40, v40
	v_rcp_f32_e32 v41, v41
	v_rcp_f32_e32 v34, v34
	v_rcp_f32_e32 v35, v35
	v_rcp_f32_e32 v36, v36
	v_rcp_f32_e32 v37, v37
	v_lshlrev_b32_e32 v143, 16, v174
	v_mul_f32_e32 v38, v38, v143
	v_lshlrev_b32_e32 v144, 16, v178
	v_mul_f32_e32 v38, v38, v144
	v_and_b32_e32 v143, 0xffff0000, v174
	v_mul_f32_e32 v39, v39, v143
	v_and_b32_e32 v144, 0xffff0000, v178
	v_mul_f32_e32 v39, v39, v144
	v_lshlrev_b32_e32 v143, 16, v175
	v_mul_f32_e32 v40, v40, v143
	v_lshlrev_b32_e32 v144, 16, v179
	v_mul_f32_e32 v40, v40, v144
	v_and_b32_e32 v143, 0xffff0000, v175
	v_mul_f32_e32 v41, v41, v143
	v_and_b32_e32 v144, 0xffff0000, v179
	v_mul_f32_e32 v41, v41, v144
	v_lshlrev_b32_e32 v143, 16, v176
	v_mul_f32_e32 v34, v34, v143
	v_lshlrev_b32_e32 v144, 16, v180
	v_mul_f32_e32 v34, v34, v144
	v_and_b32_e32 v143, 0xffff0000, v176
	v_mul_f32_e32 v35, v35, v143
	v_and_b32_e32 v144, 0xffff0000, v180
	v_mul_f32_e32 v35, v35, v144
	v_lshlrev_b32_e32 v143, 16, v177
	v_mul_f32_e32 v36, v36, v143
	v_lshlrev_b32_e32 v144, 16, v181
	v_mul_f32_e32 v36, v36, v144
	v_and_b32_e32 v143, 0xffff0000, v177
	v_mul_f32_e32 v37, v37, v143
	v_and_b32_e32 v144, 0xffff0000, v181
	v_mul_f32_e32 v37, v37, v144
	v_cvt_pk_bf16_f32 v174, v38, v39
	v_cvt_pk_bf16_f32 v175, v40, v41
	v_cvt_pk_bf16_f32 v176, v34, v35
	v_cvt_pk_bf16_f32 v177, v36, v37
	global_store_dwordx4 v142, v[174:177], s[16:17] offset:256
	v_add_u32_e32 v142, 0x8000, v142
	s_waitcnt vmcnt(13)
	v_mul_f32_e32 v30, 0xbfb8aa3b, v30
	v_mul_f32_e32 v31, 0xbfb8aa3b, v31
	v_mul_f32_e32 v32, 0xbfb8aa3b, v32
	v_mul_f32_e32 v33, 0xbfb8aa3b, v33
	v_mul_f32_e32 v26, 0xbfb8aa3b, v26
	v_mul_f32_e32 v27, 0xbfb8aa3b, v27
	v_mul_f32_e32 v28, 0xbfb8aa3b, v28
	v_mul_f32_e32 v29, 0xbfb8aa3b, v29
	v_exp_f32_e32 v30, v30
	v_exp_f32_e32 v31, v31
	v_exp_f32_e32 v32, v32
	v_exp_f32_e32 v33, v33
	v_exp_f32_e32 v26, v26
	v_exp_f32_e32 v27, v27
	v_exp_f32_e32 v28, v28
	v_exp_f32_e32 v29, v29
	v_add_f32_e32 v30, 1.0, v30
	v_add_f32_e32 v31, 1.0, v31
	v_add_f32_e32 v32, 1.0, v32
	v_add_f32_e32 v33, 1.0, v33
	v_add_f32_e32 v26, 1.0, v26
	v_add_f32_e32 v27, 1.0, v27
	v_add_f32_e32 v28, 1.0, v28
	v_add_f32_e32 v29, 1.0, v29
	v_rcp_f32_e32 v30, v30
	v_rcp_f32_e32 v31, v31
	v_rcp_f32_e32 v32, v32
	v_rcp_f32_e32 v33, v33
	v_rcp_f32_e32 v26, v26
	v_rcp_f32_e32 v27, v27
	v_rcp_f32_e32 v28, v28
	v_rcp_f32_e32 v29, v29
	v_lshlrev_b32_e32 v143, 16, v182
	v_mul_f32_e32 v30, v30, v143
	v_lshlrev_b32_e32 v144, 16, v186
	v_mul_f32_e32 v30, v30, v144
	v_and_b32_e32 v143, 0xffff0000, v182
	v_mul_f32_e32 v31, v31, v143
	v_and_b32_e32 v144, 0xffff0000, v186
	v_mul_f32_e32 v31, v31, v144
	v_lshlrev_b32_e32 v143, 16, v183
	v_mul_f32_e32 v32, v32, v143
	v_lshlrev_b32_e32 v144, 16, v187
	v_mul_f32_e32 v32, v32, v144
	v_and_b32_e32 v143, 0xffff0000, v183
	v_mul_f32_e32 v33, v33, v143
	v_and_b32_e32 v144, 0xffff0000, v187
	v_mul_f32_e32 v33, v33, v144
	v_lshlrev_b32_e32 v143, 16, v184
	v_mul_f32_e32 v26, v26, v143
	v_lshlrev_b32_e32 v144, 16, v188
	v_mul_f32_e32 v26, v26, v144
	v_and_b32_e32 v143, 0xffff0000, v184
	v_mul_f32_e32 v27, v27, v143
	v_and_b32_e32 v144, 0xffff0000, v188
	v_mul_f32_e32 v27, v27, v144
	v_lshlrev_b32_e32 v143, 16, v185
	v_mul_f32_e32 v28, v28, v143
	v_lshlrev_b32_e32 v144, 16, v189
	v_mul_f32_e32 v28, v28, v144
	v_and_b32_e32 v143, 0xffff0000, v185
	v_mul_f32_e32 v29, v29, v143
	v_and_b32_e32 v144, 0xffff0000, v189
	v_mul_f32_e32 v29, v29, v144
	v_cvt_pk_bf16_f32 v182, v30, v31
	v_cvt_pk_bf16_f32 v183, v32, v33
	v_cvt_pk_bf16_f32 v184, v26, v27
	v_cvt_pk_bf16_f32 v185, v28, v29
	global_store_dwordx4 v142, v[182:185], s[16:17]
	s_nop 0
	s_waitcnt vmcnt(11)
	v_mul_f32_e32 v22, 0xbfb8aa3b, v22
	v_mul_f32_e32 v23, 0xbfb8aa3b, v23
	v_mul_f32_e32 v24, 0xbfb8aa3b, v24
	v_mul_f32_e32 v25, 0xbfb8aa3b, v25
	v_mul_f32_e32 v18, 0xbfb8aa3b, v18
	v_mul_f32_e32 v19, 0xbfb8aa3b, v19
	v_mul_f32_e32 v20, 0xbfb8aa3b, v20
	v_mul_f32_e32 v21, 0xbfb8aa3b, v21
	v_exp_f32_e32 v22, v22
	v_exp_f32_e32 v23, v23
	v_exp_f32_e32 v24, v24
	v_exp_f32_e32 v25, v25
	v_exp_f32_e32 v18, v18
	v_exp_f32_e32 v19, v19
	v_exp_f32_e32 v20, v20
	v_exp_f32_e32 v21, v21
	v_add_f32_e32 v22, 1.0, v22
	v_add_f32_e32 v23, 1.0, v23
	v_add_f32_e32 v24, 1.0, v24
	v_add_f32_e32 v25, 1.0, v25
	v_add_f32_e32 v18, 1.0, v18
	v_add_f32_e32 v19, 1.0, v19
	v_add_f32_e32 v20, 1.0, v20
	v_add_f32_e32 v21, 1.0, v21
	v_rcp_f32_e32 v22, v22
	v_rcp_f32_e32 v23, v23
	v_rcp_f32_e32 v24, v24
	v_rcp_f32_e32 v25, v25
	v_rcp_f32_e32 v18, v18
	v_rcp_f32_e32 v19, v19
	v_rcp_f32_e32 v20, v20
	v_rcp_f32_e32 v21, v21
	v_lshlrev_b32_e32 v143, 16, v190
	v_mul_f32_e32 v22, v22, v143
	v_lshlrev_b32_e32 v144, 16, v194
	v_mul_f32_e32 v22, v22, v144
	v_and_b32_e32 v143, 0xffff0000, v190
	v_mul_f32_e32 v23, v23, v143
	v_and_b32_e32 v144, 0xffff0000, v194
	v_mul_f32_e32 v23, v23, v144
	v_lshlrev_b32_e32 v143, 16, v191
	v_mul_f32_e32 v24, v24, v143
	v_lshlrev_b32_e32 v144, 16, v195
	v_mul_f32_e32 v24, v24, v144
	v_and_b32_e32 v143, 0xffff0000, v191
	v_mul_f32_e32 v25, v25, v143
	v_and_b32_e32 v144, 0xffff0000, v195
	v_mul_f32_e32 v25, v25, v144
	v_lshlrev_b32_e32 v143, 16, v192
	v_mul_f32_e32 v18, v18, v143
	v_lshlrev_b32_e32 v144, 16, v196
	v_mul_f32_e32 v18, v18, v144
	v_and_b32_e32 v143, 0xffff0000, v192
	v_mul_f32_e32 v19, v19, v143
	v_and_b32_e32 v144, 0xffff0000, v196
	v_mul_f32_e32 v19, v19, v144
	v_lshlrev_b32_e32 v143, 16, v193
	v_mul_f32_e32 v20, v20, v143
	v_lshlrev_b32_e32 v144, 16, v197
	v_mul_f32_e32 v20, v20, v144
	v_and_b32_e32 v143, 0xffff0000, v193
	v_mul_f32_e32 v21, v21, v143
	v_and_b32_e32 v144, 0xffff0000, v197
	v_mul_f32_e32 v21, v21, v144
	v_cvt_pk_bf16_f32 v190, v22, v23
	v_cvt_pk_bf16_f32 v191, v24, v25
	v_cvt_pk_bf16_f32 v192, v18, v19
	v_cvt_pk_bf16_f32 v193, v20, v21
	global_store_dwordx4 v142, v[190:193], s[16:17] offset:256
	v_add_u32_e32 v142, 0x8000, v142
	s_waitcnt vmcnt(9)
	v_mul_f32_e32 v14, 0xbfb8aa3b, v14
	v_mul_f32_e32 v15, 0xbfb8aa3b, v15
	v_mul_f32_e32 v16, 0xbfb8aa3b, v16
	v_mul_f32_e32 v17, 0xbfb8aa3b, v17
	v_mul_f32_e32 v10, 0xbfb8aa3b, v10
	v_mul_f32_e32 v11, 0xbfb8aa3b, v11
	v_mul_f32_e32 v12, 0xbfb8aa3b, v12
	v_mul_f32_e32 v13, 0xbfb8aa3b, v13
	v_exp_f32_e32 v14, v14
	v_exp_f32_e32 v15, v15
	v_exp_f32_e32 v16, v16
	v_exp_f32_e32 v17, v17
	v_exp_f32_e32 v10, v10
	v_exp_f32_e32 v11, v11
	v_exp_f32_e32 v12, v12
	v_exp_f32_e32 v13, v13
	v_add_f32_e32 v14, 1.0, v14
	v_add_f32_e32 v15, 1.0, v15
	v_add_f32_e32 v16, 1.0, v16
	v_add_f32_e32 v17, 1.0, v17
	v_add_f32_e32 v10, 1.0, v10
	v_add_f32_e32 v11, 1.0, v11
	v_add_f32_e32 v12, 1.0, v12
	v_add_f32_e32 v13, 1.0, v13
	v_rcp_f32_e32 v14, v14
	v_rcp_f32_e32 v15, v15
	v_rcp_f32_e32 v16, v16
	v_rcp_f32_e32 v17, v17
	v_rcp_f32_e32 v10, v10
	v_rcp_f32_e32 v11, v11
	v_rcp_f32_e32 v12, v12
	v_rcp_f32_e32 v13, v13
	v_lshlrev_b32_e32 v143, 16, v224
	v_mul_f32_e32 v14, v14, v143
	v_lshlrev_b32_e32 v144, 16, v228
	v_mul_f32_e32 v14, v14, v144
	v_and_b32_e32 v143, 0xffff0000, v224
	v_mul_f32_e32 v15, v15, v143
	v_and_b32_e32 v144, 0xffff0000, v228
	v_mul_f32_e32 v15, v15, v144
	v_lshlrev_b32_e32 v143, 16, v225
	v_mul_f32_e32 v16, v16, v143
	v_lshlrev_b32_e32 v144, 16, v229
	v_mul_f32_e32 v16, v16, v144
	v_and_b32_e32 v143, 0xffff0000, v225
	v_mul_f32_e32 v17, v17, v143
	v_and_b32_e32 v144, 0xffff0000, v229
	v_mul_f32_e32 v17, v17, v144
	v_lshlrev_b32_e32 v143, 16, v226
	v_mul_f32_e32 v10, v10, v143
	v_lshlrev_b32_e32 v144, 16, v230
	v_mul_f32_e32 v10, v10, v144
	v_and_b32_e32 v143, 0xffff0000, v226
	v_mul_f32_e32 v11, v11, v143
	v_and_b32_e32 v144, 0xffff0000, v230
	v_mul_f32_e32 v11, v11, v144
	v_lshlrev_b32_e32 v143, 16, v227
	v_mul_f32_e32 v12, v12, v143
	v_lshlrev_b32_e32 v144, 16, v231
	v_mul_f32_e32 v12, v12, v144
	v_and_b32_e32 v143, 0xffff0000, v227
	v_mul_f32_e32 v13, v13, v143
	v_and_b32_e32 v144, 0xffff0000, v231
	v_mul_f32_e32 v13, v13, v144
	v_cvt_pk_bf16_f32 v224, v14, v15
	v_cvt_pk_bf16_f32 v225, v16, v17
	v_cvt_pk_bf16_f32 v226, v10, v11
	v_cvt_pk_bf16_f32 v227, v12, v13
	global_store_dwordx4 v142, v[224:227], s[16:17]
	s_nop 0
	s_waitcnt vmcnt(7)
	v_mul_f32_e32 v6, 0xbfb8aa3b, v6
	v_mul_f32_e32 v7, 0xbfb8aa3b, v7
	v_mul_f32_e32 v8, 0xbfb8aa3b, v8
	v_mul_f32_e32 v9, 0xbfb8aa3b, v9
	v_mul_f32_e32 v2, 0xbfb8aa3b, v2
	v_mul_f32_e32 v3, 0xbfb8aa3b, v3
	v_mul_f32_e32 v4, 0xbfb8aa3b, v4
	v_mul_f32_e32 v5, 0xbfb8aa3b, v5
	v_exp_f32_e32 v6, v6
	v_exp_f32_e32 v7, v7
	v_exp_f32_e32 v8, v8
	v_exp_f32_e32 v9, v9
	v_exp_f32_e32 v2, v2
	v_exp_f32_e32 v3, v3
	v_exp_f32_e32 v4, v4
	v_exp_f32_e32 v5, v5
	v_add_f32_e32 v6, 1.0, v6
	v_add_f32_e32 v7, 1.0, v7
	v_add_f32_e32 v8, 1.0, v8
	v_add_f32_e32 v9, 1.0, v9
	v_add_f32_e32 v2, 1.0, v2
	v_add_f32_e32 v3, 1.0, v3
	v_add_f32_e32 v4, 1.0, v4
	v_add_f32_e32 v5, 1.0, v5
	v_rcp_f32_e32 v6, v6
	v_rcp_f32_e32 v7, v7
	v_rcp_f32_e32 v8, v8
	v_rcp_f32_e32 v9, v9
	v_rcp_f32_e32 v2, v2
	v_rcp_f32_e32 v3, v3
	v_rcp_f32_e32 v4, v4
	v_rcp_f32_e32 v5, v5
	v_lshlrev_b32_e32 v143, 16, v232
	v_mul_f32_e32 v6, v6, v143
	v_lshlrev_b32_e32 v144, 16, v236
	v_mul_f32_e32 v6, v6, v144
	v_and_b32_e32 v143, 0xffff0000, v232
	v_mul_f32_e32 v7, v7, v143
	v_and_b32_e32 v144, 0xffff0000, v236
	v_mul_f32_e32 v7, v7, v144
	v_lshlrev_b32_e32 v143, 16, v233
	v_mul_f32_e32 v8, v8, v143
	v_lshlrev_b32_e32 v144, 16, v237
	v_mul_f32_e32 v8, v8, v144
	v_and_b32_e32 v143, 0xffff0000, v233
	v_mul_f32_e32 v9, v9, v143
	v_and_b32_e32 v144, 0xffff0000, v237
	v_mul_f32_e32 v9, v9, v144
	v_lshlrev_b32_e32 v143, 16, v234
	v_mul_f32_e32 v2, v2, v143
	v_lshlrev_b32_e32 v144, 16, v238
	v_mul_f32_e32 v2, v2, v144
	v_and_b32_e32 v143, 0xffff0000, v234
	v_mul_f32_e32 v3, v3, v143
	v_and_b32_e32 v144, 0xffff0000, v238
	v_mul_f32_e32 v3, v3, v144
	v_lshlrev_b32_e32 v143, 16, v235
	v_mul_f32_e32 v4, v4, v143
	v_lshlrev_b32_e32 v144, 16, v239
	v_mul_f32_e32 v4, v4, v144
	v_and_b32_e32 v143, 0xffff0000, v235
	v_mul_f32_e32 v5, v5, v143
	v_and_b32_e32 v144, 0xffff0000, v239
	v_mul_f32_e32 v5, v5, v144
	v_cvt_pk_bf16_f32 v232, v6, v7
	v_cvt_pk_bf16_f32 v233, v8, v9
	v_cvt_pk_bf16_f32 v234, v2, v3
	v_cvt_pk_bf16_f32 v235, v4, v5
	global_store_dwordx4 v142, v[232:235], s[16:17] offset:256
	s_nop 0
	s_mov_b64 s[2:3], -1
	s_andn2_b64 vcc, exec, s[38:39]
	s_cbranch_vccnz .LBB0_842
	s_andn2_b64 vcc, exec, s[0:1]
	s_cbranch_vccnz .LBB0_841
	s_barrier
	s_branch .LBB0_841
